# defer all 22016 w_down conversion items into P1 tail
# baseline (speedup 1.0000x reference)
.LBB0_9:
	s_cmp_lg_u32 s101, 0
	s_cbranch_scc1 .Lcv_go
	s_cmp_lt_i32 s80, 0x15480
	s_cbranch_scc1 .Lcv_go
	s_cmp_lt_i32 s80, 0x1aa80
	s_cbranch_scc1 .LBB0_8

.LBB0_415:
	s_waitcnt vmcnt(0)
	s_barrier
	v_writelane_b32 v248, s0, 0
	v_writelane_b32 v248, s1, 1
	v_writelane_b32 v248, s2, 2
	v_writelane_b32 v248, s3, 3
	v_writelane_b32 v248, s4, 4
	v_writelane_b32 v248, s5, 5
	v_writelane_b32 v248, s6, 6
	v_writelane_b32 v248, s7, 7
	v_writelane_b32 v248, s8, 8
	v_writelane_b32 v248, s9, 9
	v_writelane_b32 v248, s10, 10
	v_writelane_b32 v248, s11, 11
	v_writelane_b32 v248, s12, 12
	v_writelane_b32 v248, s13, 13
	v_writelane_b32 v248, s14, 14
	v_writelane_b32 v248, s15, 15
	v_writelane_b32 v248, s16, 16
	v_writelane_b32 v248, s17, 17
	v_writelane_b32 v248, s18, 18
	v_writelane_b32 v248, s19, 19
	v_writelane_b32 v248, s20, 20
	v_writelane_b32 v248, s21, 21
	v_writelane_b32 v248, s22, 22
	v_writelane_b32 v248, s23, 23
	v_writelane_b32 v248, s24, 24
	v_writelane_b32 v248, s25, 25
	v_writelane_b32 v248, s26, 26
	v_writelane_b32 v248, s27, 27
	v_writelane_b32 v248, s28, 28
	v_writelane_b32 v248, s29, 29
	v_writelane_b32 v248, s30, 30
	v_writelane_b32 v248, s31, 31
	v_writelane_b32 v248, s32, 32
	v_writelane_b32 v248, s33, 33
	v_writelane_b32 v248, s34, 34
	v_writelane_b32 v248, s35, 35
	v_writelane_b32 v248, s36, 36
	v_writelane_b32 v248, s37, 37
	v_writelane_b32 v248, s38, 38
	v_writelane_b32 v248, s39, 39
	v_writelane_b32 v248, s40, 40
	v_writelane_b32 v248, s41, 41
	v_writelane_b32 v248, s42, 42
	v_writelane_b32 v248, s43, 43
	v_writelane_b32 v248, s44, 44
	v_writelane_b32 v248, s45, 45
	v_writelane_b32 v248, s46, 46
	v_writelane_b32 v248, s47, 47
	v_writelane_b32 v248, s48, 48
	v_writelane_b32 v248, s49, 49
	v_writelane_b32 v248, s50, 50
	v_writelane_b32 v248, s51, 51
	v_writelane_b32 v248, s52, 52
	v_writelane_b32 v248, s53, 53
	v_writelane_b32 v248, s54, 54
	v_writelane_b32 v248, s55, 55
	v_writelane_b32 v248, s56, 56
	v_writelane_b32 v248, s57, 57
	v_writelane_b32 v248, s58, 58
	v_writelane_b32 v248, s59, 59
	v_writelane_b32 v248, s60, 60
	v_writelane_b32 v248, s61, 61
	v_writelane_b32 v248, s62, 62
	v_writelane_b32 v248, s63, 63
	v_writelane_b32 v249, s64, 0
	v_writelane_b32 v249, s65, 1
	v_writelane_b32 v249, s66, 2
	v_writelane_b32 v249, s67, 3
	v_writelane_b32 v249, s68, 4
	v_writelane_b32 v249, s69, 5
	v_writelane_b32 v249, s70, 6
	v_writelane_b32 v249, s71, 7
	v_writelane_b32 v249, s72, 8
	v_writelane_b32 v249, s73, 9
	v_writelane_b32 v249, s74, 10
	v_writelane_b32 v249, s75, 11
	v_writelane_b32 v249, s76, 12
	v_writelane_b32 v249, s77, 13
	v_writelane_b32 v249, s78, 14
	v_writelane_b32 v249, s79, 15
	v_writelane_b32 v249, s80, 16
	v_writelane_b32 v249, s81, 17
	v_writelane_b32 v249, s82, 18
	v_writelane_b32 v249, s83, 19
	v_writelane_b32 v249, s84, 20
	v_writelane_b32 v249, s85, 21
	v_writelane_b32 v249, s86, 22
	v_writelane_b32 v249, s87, 23
	v_writelane_b32 v249, s88, 24
	v_writelane_b32 v249, s89, 25
	v_writelane_b32 v249, s90, 26
	v_writelane_b32 v249, s91, 27
	v_writelane_b32 v249, s92, 28
	v_writelane_b32 v249, s93, 29
	v_writelane_b32 v249, s94, 30
	v_writelane_b32 v249, s95, 31
	v_writelane_b32 v249, s96, 32
	v_writelane_b32 v249, s97, 33
	v_readlane_b32 s1, v250, 9
	v_readlane_b32 s86, v250, 10
	v_readlane_b32 s87, v250, 11
	s_sub_i32 s0, s2, 0x74
	s_lshl_b32 s0, s0, 3
	s_nop 1
	s_add_i32 s12, s0, s1
	s_add_i32 s12, s12, 0x15480
	s_movk_i32 s14, 0x460
	s_mov_b32 s100, 0x1aa80
	s_mov_b32 s101, 1
	s_branch .Lcv_entry
